# stagger: waves 4-7 s_sleep 5 after each tile barrier in lockstep attention loops (NSA window, compressed pass2, moba own, moba gather)
# baseline (speedup 1.0000x reference)
; DI void moba_gather_phase(int ws, PP p, char* shm) {
;     ...
;     if (tid == 0) *gslot = (int)atomicAdd(p->ctr + 2, 1u);
;     f32x16 o[2];
; #pragma unroll
;     for (int db = 0; db < 2; ++db)
; #pragma unroll
;       for (int i = 0; i < 16; ++i) o[db][i] = 0.f;
;     float m = -1e30f, l = 0.f;
;     __syncthreads();
;     const int itn = *gslot;
.LBB0_739:
	s_or_b64 exec, exec, s[14:15]
	s_waitcnt lgkmcnt(0)
	s_barrier
	s_cselect_b32 s101, 1, 0
	s_cmp_lt_u32 s33, 0x100
	s_cbranch_scc1 .Lstg_gat
	s_sleep 5
.Lstg_gat:
	s_cmp_eq_u32 s101, 1
	ds_read_b32 v28, v162
	s_waitcnt lgkmcnt(0)
	v_cmp_ge_i32_e64 s[14:15], v28, v159
	v_readfirstlane_b32 s4, v28
	v_cmp_lt_i32_e64 s[16:17], v28, v159
	s_and_b64 vcc, exec, s[14:15]
	s_cbranch_vccnz .LBB0_743
	s_movk_i32 s5, 0x400
	s_mov_b32 s34, 0

; DI uint32_t range_mask(int kpos0, int lo, int hi, int hh) {
;   if (kpos0 >= lo && kpos0 + 63 <= hi) return 0xffffffffu;
;   if (kpos0 > hi || kpos0 + 63 < lo) return 0u;
;   uint32_t vm = 0;
; #pragma unroll
;   for (int kb = 0; kb < 2; ++kb)
; #pragma unroll
;     for (int i = 0; i < 16; ++i) {
;       int kp = kpos0 + kb * 32 + hh * 4 + (i & 3) + 8 * (i >> 2);
;       vm |= (kp >= lo && kp <= hi) ? (1u << (kb * 16 + i)) : 0u;
;     }
;   return vm;
; }
.LBB0_791:
	global_load_dwordx4 v[112:115], v[132:133], off
	global_load_dwordx4 v[116:119], v[130:131], off
	s_cmp_lt_u32 s33, 0x100
	s_cbranch_scc1 .Lstg_own
	s_sleep 5
.Lstg_own:
	s_add_i32 s10, s4, 63
	v_cmp_gt_i32_e32 vcc, s10, v164
	v_mov_b32_e32 v48, -1
	s_and_saveexec_b64 s[10:11], vcc
	s_cbranch_execz .LBB0_795
	v_cmp_le_i32_e32 vcc, s4, v164
	v_mov_b32_e32 v48, 0
	s_and_saveexec_b64 s[12:13], vcc
	s_cbranch_execz .LBB0_794
	v_add_u32_e32 v32, s4, v124
	v_cmp_le_i32_e32 vcc, v32, v164
	v_add_u32_e32 v35, 3, v32
	s_nop 0
	v_cndmask_b32_e64 v33, 0, 1, vcc
	v_cmp_lt_i32_e32 vcc, v32, v164
	s_nop 1
	v_cndmask_b32_e64 v34, 0, 2, vcc
	v_or_b32_e32 v33, v34, v33
	v_add_u32_e32 v34, 2, v32
	v_cmp_gt_i32_e32 vcc, v34, v164
	s_nop 1
	v_cndmask_b32_e64 v34, 4, 0, vcc
	v_cmp_gt_i32_e32 vcc, v35, v164
	s_nop 1
	v_cndmask_b32_e64 v35, 8, 0, vcc
	v_or3_b32 v33, v33, v34, v35
	v_add_u32_e32 v34, 8, v32
	v_cmp_gt_i32_e32 vcc, v34, v164
	v_add_u32_e32 v35, 9, v32
	s_nop 0
	v_cndmask_b32_e64 v34, 16, 0, vcc
	v_cmp_gt_i32_e32 vcc, v35, v164
	s_nop 1
	v_cndmask_b32_e64 v35, 32, 0, vcc
	v_or3_b32 v33, v33, v34, v35
	v_add_u32_e32 v34, 10, v32
	v_cmp_gt_i32_e32 vcc, v34, v164
	v_add_u32_e32 v35, 11, v32
	s_nop 0
	v_cndmask_b32_e64 v34, 64, 0, vcc
	v_cmp_gt_i32_e32 vcc, v35, v164
	s_nop 1
	v_cndmask_b32_e64 v35, v136, 0, vcc
	v_or3_b32 v33, v33, v34, v35
	v_add_u32_e32 v34, 16, v32
	v_cmp_gt_i32_e32 vcc, v34, v164
	v_add_u32_e32 v35, 17, v32
	s_nop 0
	v_cndmask_b32_e64 v34, v137, 0, vcc
	v_cmp_gt_i32_e32 vcc, v35, v164
	s_nop 1
	v_cndmask_b32_e64 v35, v138, 0, vcc
	v_or3_b32 v33, v33, v34, v35
	v_add_u32_e32 v34, 18, v32
	v_cmp_gt_i32_e32 vcc, v34, v164
	v_add_u32_e32 v35, 19, v32
	s_nop 0
	v_cndmask_b32_e64 v34, v139, 0, vcc
	v_cmp_gt_i32_e32 vcc, v35, v164
	s_nop 1
	v_cndmask_b32_e64 v35, v140, 0, vcc
	v_or3_b32 v33, v33, v34, v35
	v_add_u32_e32 v34, 24, v32
	v_cmp_gt_i32_e32 vcc, v34, v164
	v_add_u32_e32 v35, 25, v32
	s_nop 0
	v_cndmask_b32_e64 v34, v141, 0, vcc
	v_cmp_gt_i32_e32 vcc, v35, v164
	s_nop 1
	v_cndmask_b32_e64 v35, v142, 0, vcc
	v_or3_b32 v33, v33, v34, v35
	v_add_u32_e32 v34, 26, v32
	v_cmp_gt_i32_e32 vcc, v34, v164
	v_add_u32_e32 v35, 27, v32
	s_nop 0
	v_cndmask_b32_e64 v34, v143, 0, vcc
	v_cmp_gt_i32_e32 vcc, v35, v164
	s_nop 1
	v_cndmask_b32_e64 v35, v144, 0, vcc
	v_or3_b32 v33, v33, v34, v35
	v_add_u32_e32 v34, 32, v32
	v_cmp_gt_i32_e32 vcc, v34, v164
	v_add_u32_e32 v35, 33, v32
	s_nop 0
	v_cndmask_b32_e64 v34, v145, 0, vcc
	v_cmp_gt_i32_e32 vcc, v35, v164
	s_nop 1
	v_cndmask_b32_e64 v35, v146, 0, vcc
	v_or3_b32 v33, v33, v34, v35
	v_add_u32_e32 v34, 34, v32
	v_cmp_gt_i32_e32 vcc, v34, v164
	v_add_u32_e32 v35, 35, v32
	s_nop 0
	v_cndmask_b32_e64 v34, v147, 0, vcc
	v_cmp_gt_i32_e32 vcc, v35, v164
	s_nop 1
	v_cndmask_b32_e64 v35, v148, 0, vcc
	v_or3_b32 v33, v33, v34, v35
	v_add_u32_e32 v34, 40, v32
	v_cmp_gt_i32_e32 vcc, v34, v164
	v_add_u32_e32 v35, 41, v32
	s_nop 0
	v_cndmask_b32_e64 v34, v149, 0, vcc
	v_cmp_gt_i32_e32 vcc, v35, v164
	s_nop 1
	v_cndmask_b32_e64 v35, v150, 0, vcc
	v_or3_b32 v33, v33, v34, v35
	v_add_u32_e32 v34, 42, v32
	v_cmp_gt_i32_e32 vcc, v34, v164
	v_add_u32_e32 v35, 43, v32
	s_nop 0
	v_cndmask_b32_e64 v34, v151, 0, vcc
	v_cmp_gt_i32_e32 vcc, v35, v164
	s_nop 1
	v_cndmask_b32_e64 v35, v152, 0, vcc
	v_or3_b32 v33, v33, v34, v35
	v_add_u32_e32 v34, 48, v32
	v_cmp_gt_i32_e32 vcc, v34, v164
	v_add_u32_e32 v35, 49, v32
	s_nop 0
	v_cndmask_b32_e64 v34, v153, 0, vcc
	v_cmp_gt_i32_e32 vcc, v35, v164
	s_nop 1
	v_cndmask_b32_e64 v35, v154, 0, vcc
	v_or3_b32 v33, v33, v34, v35
	v_add_u32_e32 v34, 50, v32
	v_cmp_gt_i32_e32 vcc, v34, v164
	v_add_u32_e32 v35, 51, v32
	s_nop 0
	v_cndmask_b32_e64 v34, v155, 0, vcc
	v_cmp_gt_i32_e32 vcc, v35, v164
	s_nop 1
	v_cndmask_b32_e64 v35, v156, 0, vcc
	v_or3_b32 v33, v33, v34, v35
	v_add_u32_e32 v34, 56, v32
	v_cmp_gt_i32_e32 vcc, v34, v164
	v_add_u32_e32 v35, 57, v32
	s_nop 0
	v_cndmask_b32_e64 v34, v157, 0, vcc
	v_cmp_gt_i32_e32 vcc, v35, v164
	s_nop 1
	v_cndmask_b32_e64 v35, v158, 0, vcc
	v_or3_b32 v33, v33, v34, v35
	v_add_u32_e32 v34, 58, v32
	v_cmp_gt_i32_e32 vcc, v34, v164
	v_add_u32_e32 v32, 59, v32
	s_nop 0
	v_cndmask_b32_e64 v34, 2.0, 0, vcc
	v_cmp_gt_i32_e32 vcc, v32, v164
	s_nop 1
	v_cndmask_b32_e64 v32, v159, 0, vcc
	v_or3_b32 v48, v33, v34, v32

; DI uint32_t range_mask(int kpos0, int lo, int hi, int hh) {
;   if (kpos0 >= lo && kpos0 + 63 <= hi) return 0xffffffffu;
;   if (kpos0 > hi || kpos0 + 63 < lo) return 0u;
;   uint32_t vm = 0;
; #pragma unroll
;   for (int kb = 0; kb < 2; ++kb)
; #pragma unroll
;     for (int i = 0; i < 16; ++i) {
;       int kp = kpos0 + kb * 32 + hh * 4 + (i & 3) + 8 * (i >> 2);
;       vm |= (kp >= lo && kp <= hi) ? (1u << (kb * 16 + i)) : 0u;
;     }
;   return vm;
; }
; DI void nsa_item(int ws, PP p, char* shm, int item) {
;     ...
;     auto body2 = [&](int i, const u16* Ks, const u16* Vs) {
;       const uint32_t vm = range_mask(i * 64, 0, cmax, hh);
;       f32x16 s[2];
;       qk_tile(Ks, qn, s, rl, hh);
.LBB0_1606:
	s_cselect_b32 s101, 1, 0
	s_cmp_lt_u32 s33, 0x100
	s_cbranch_scc1 .Lstg_p2
	s_sleep 5
.Lstg_p2:
	s_cmp_eq_u32 s101, 1
	s_add_i32 s14, s5, 63
	v_cmp_gt_i32_e32 vcc, s14, v123
	v_mov_b32_e32 v12, -1
	s_and_saveexec_b64 s[14:15], vcc
	s_cbranch_execz .LBB0_1610
	v_cmp_le_i32_e32 vcc, s5, v123
	v_mov_b32_e32 v12, 0
	s_and_saveexec_b64 s[16:17], vcc
	s_cbranch_execz .LBB0_1609
	v_add_u32_e32 v12, s5, v193
	v_cmp_le_i32_e32 vcc, v12, v123
	v_add_u32_e32 v15, 3, v12
	s_nop 0
	v_cndmask_b32_e64 v13, 0, 1, vcc
	v_cmp_lt_i32_e32 vcc, v12, v123
	s_nop 1
	v_cndmask_b32_e64 v14, 0, 2, vcc
	v_or_b32_e32 v13, v14, v13
	v_add_u32_e32 v14, 2, v12
	v_cmp_gt_i32_e32 vcc, v14, v123
	s_nop 1
	v_cndmask_b32_e64 v14, 4, 0, vcc
	v_cmp_gt_i32_e32 vcc, v15, v123
	s_nop 1
	v_cndmask_b32_e64 v15, 8, 0, vcc
	v_or3_b32 v13, v13, v14, v15
	v_add_u32_e32 v14, 8, v12
	v_cmp_gt_i32_e32 vcc, v14, v123
	v_add_u32_e32 v15, 9, v12
	s_nop 0
	v_cndmask_b32_e64 v14, 16, 0, vcc
	v_cmp_gt_i32_e32 vcc, v15, v123
	s_nop 1
	v_cndmask_b32_e64 v15, 32, 0, vcc
	v_or3_b32 v13, v13, v14, v15
	v_add_u32_e32 v14, 10, v12
	v_cmp_gt_i32_e32 vcc, v14, v123
	v_add_u32_e32 v15, 11, v12
	s_nop 0
	v_cndmask_b32_e64 v14, 64, 0, vcc
	v_cmp_gt_i32_e32 vcc, v15, v123
	s_nop 1
	v_cndmask_b32_e64 v15, v205, 0, vcc
	v_or3_b32 v13, v13, v14, v15
	v_add_u32_e32 v14, 16, v12
	v_cmp_gt_i32_e32 vcc, v14, v123
	v_add_u32_e32 v15, 17, v12
	s_nop 0
	v_cndmask_b32_e64 v14, v206, 0, vcc
	v_cmp_gt_i32_e32 vcc, v15, v123
	s_nop 1
	v_cndmask_b32_e64 v15, v207, 0, vcc
	v_or3_b32 v13, v13, v14, v15
	v_add_u32_e32 v14, 18, v12
	v_cmp_gt_i32_e32 vcc, v14, v123
	v_add_u32_e32 v15, 19, v12
	s_nop 0
	v_cndmask_b32_e64 v14, v208, 0, vcc
	v_cmp_gt_i32_e32 vcc, v15, v123
	s_nop 1
	v_cndmask_b32_e64 v15, v209, 0, vcc
	v_or3_b32 v13, v13, v14, v15
	v_add_u32_e32 v14, 24, v12
	v_cmp_gt_i32_e32 vcc, v14, v123
	v_add_u32_e32 v15, 25, v12
	s_nop 0
	v_cndmask_b32_e64 v14, v210, 0, vcc
	v_cmp_gt_i32_e32 vcc, v15, v123
	s_nop 1
	v_cndmask_b32_e64 v15, v211, 0, vcc
	v_or3_b32 v13, v13, v14, v15
	v_add_u32_e32 v14, 26, v12
	v_cmp_gt_i32_e32 vcc, v14, v123
	v_add_u32_e32 v15, 27, v12
	s_nop 0
	v_cndmask_b32_e64 v14, v212, 0, vcc
	v_cmp_gt_i32_e32 vcc, v15, v123
	s_nop 1
	v_cndmask_b32_e64 v15, v213, 0, vcc
	v_or3_b32 v13, v13, v14, v15
	v_add_u32_e32 v14, 32, v12
	v_cmp_gt_i32_e32 vcc, v14, v123
	v_add_u32_e32 v15, 33, v12
	s_nop 0
	v_cndmask_b32_e64 v14, v214, 0, vcc
	v_cmp_gt_i32_e32 vcc, v15, v123
	s_nop 1
	v_cndmask_b32_e64 v15, v215, 0, vcc
	v_or3_b32 v13, v13, v14, v15
	v_add_u32_e32 v14, 34, v12
	v_cmp_gt_i32_e32 vcc, v14, v123
	v_add_u32_e32 v15, 35, v12
	s_nop 0
	v_cndmask_b32_e64 v14, v216, 0, vcc
	v_cmp_gt_i32_e32 vcc, v15, v123
	s_nop 1
	v_cndmask_b32_e64 v15, v217, 0, vcc
	v_or3_b32 v13, v13, v14, v15
	v_add_u32_e32 v14, 40, v12
	v_cmp_gt_i32_e32 vcc, v14, v123
	v_add_u32_e32 v15, 41, v12
	s_nop 0
	v_cndmask_b32_e64 v14, v218, 0, vcc
	v_cmp_gt_i32_e32 vcc, v15, v123
	s_nop 1
	v_cndmask_b32_e64 v15, v219, 0, vcc
	v_or3_b32 v13, v13, v14, v15
	v_add_u32_e32 v14, 42, v12
	v_cmp_gt_i32_e32 vcc, v14, v123
	v_add_u32_e32 v15, 43, v12
	s_nop 0
	v_cndmask_b32_e64 v14, v220, 0, vcc
	v_cmp_gt_i32_e32 vcc, v15, v123
	s_nop 1
	v_cndmask_b32_e64 v15, v221, 0, vcc
	v_or3_b32 v13, v13, v14, v15
	v_add_u32_e32 v14, 48, v12
	v_cmp_gt_i32_e32 vcc, v14, v123
	v_add_u32_e32 v15, 49, v12
	s_nop 0
	v_cndmask_b32_e64 v14, v222, 0, vcc
	v_cmp_gt_i32_e32 vcc, v15, v123
	s_nop 1
	v_cndmask_b32_e64 v15, v223, 0, vcc
	v_or3_b32 v13, v13, v14, v15
	v_add_u32_e32 v14, 50, v12
	v_cmp_gt_i32_e32 vcc, v14, v123
	v_add_u32_e32 v15, 51, v12
	s_nop 0
	v_cndmask_b32_e64 v14, v224, 0, vcc
	v_cmp_gt_i32_e32 vcc, v15, v123
	s_nop 1
	v_cndmask_b32_e64 v15, v225, 0, vcc
	v_or3_b32 v13, v13, v14, v15
	v_add_u32_e32 v14, 56, v12
	v_cmp_gt_i32_e32 vcc, v14, v123
	v_add_u32_e32 v15, 57, v12
	s_nop 0
	v_cndmask_b32_e64 v14, v226, 0, vcc
	v_cmp_gt_i32_e32 vcc, v15, v123
	s_nop 1
	v_cndmask_b32_e64 v15, v227, 0, vcc
	v_or3_b32 v13, v13, v14, v15
	v_add_u32_e32 v14, 58, v12
	v_cmp_gt_i32_e32 vcc, v14, v123
	v_add_u32_e32 v12, 59, v12
	s_nop 0
	v_cndmask_b32_e64 v14, 2.0, 0, vcc
	v_cmp_gt_i32_e32 vcc, v12, v123
	s_nop 1
	v_cndmask_b32_e64 v12, v238, 0, vcc
	v_or3_b32 v12, v13, v14, v12

; DI void nsa_item(int ws, PP p, char* shm, int item) {
;     ...
;     auto body = [&](int i, const u16* Ks, const u16* Vs) {
;       const int j = jlo + i;
;       const uint32_t vm = range_mask(j * 64, tok - 511, tok, hh);
;       if (__ballot(vm != 0) != 0ull) {
;         f32x16 s[2];
;         qk_tile(Ks, qr, s, rl, hh);
;         online_softmax(s, vm, m, l, o);
;         pv_tile(Vs, s, o, rl, hh);
;       }
;     };
.LBB0_1774:
	s_cmp_lt_u32 s33, 0x100
	s_cbranch_scc1 .Lstg_win
	s_sleep 5
